# attention fast path extended to the masked (diagonal) key tiles: per-row reference advance D_row = med3(cum(first key) - cumq, 0, D_tile), masked keys get C = -1e30 before QK^T; on top of v056
# speedup vs baseline: 1.0029x; 1.0002x over previous
.LBB0_873:
	s_cmpk_eq_i32 s71, 0xffd0
	s_cselect_b64 s[34:35], -1, 0
	s_and_b64 s[4:5], s[34:35], exec
	s_cselect_b32 s84, 0, s71
	s_cmp_gt_i32 s84, s29
	s_cselect_b64 s[4:5], -1, 0
	s_or_b64 s[4:5], s[58:59], s[4:5]
	s_and_b64 vcc, exec, s[4:5]
	s_cbranch_vccnz .LBB0_883
	s_and_b64 vcc, exec, s[34:35]
	s_cbranch_vccnz .Lattn_orig
	s_add_i32 s4, s84, 63
	s_cmp_gt_i32 s4, s95
	s_cselect_b64 s[74:75], -1, 0
	ds_read_b128 v[88:91], v221
	ds_read_b128 v[92:95], v221 offset:64
	ds_read_b128 v[164:167], v221 offset:576
	ds_read_b128 v[168:171], v221 offset:640
	ds_read_b128 v[172:175], v221 offset:4608
	ds_read_b128 v[236:239], v221 offset:4672
	ds_read_b128 v[240:243], v221 offset:5184
	ds_read_b128 v[160:163], v221 offset:5248
	v_readlane_b32 s4, v84, 0
	v_readlane_b32 s5, v75, 63
	v_pk_add_f32 v[116:117], v[140:141], v[84:85] neg_lo:[0,1] neg_hi:[0,1]
	v_pk_add_f32 v[118:119], v[140:141], v[86:87] neg_lo:[0,1] neg_hi:[0,1]
	v_pk_add_f32 v[100:101], v[142:143], v[84:85] neg_lo:[0,1] neg_hi:[0,1]
	v_pk_add_f32 v[102:103], v[142:143], v[86:87] neg_lo:[0,1] neg_hi:[0,1]
	v_pk_add_f32 v[112:113], v[140:141], v[76:77] neg_lo:[0,1] neg_hi:[0,1]
	v_pk_add_f32 v[114:115], v[140:141], v[78:79] neg_lo:[0,1] neg_hi:[0,1]
	v_pk_add_f32 v[96:97], v[142:143], v[76:77] neg_lo:[0,1] neg_hi:[0,1]
	v_pk_add_f32 v[98:99], v[142:143], v[78:79] neg_lo:[0,1] neg_hi:[0,1]
	v_pk_add_f32 v[108:109], v[140:141], v[80:81] neg_lo:[0,1] neg_hi:[0,1]
	v_pk_add_f32 v[110:111], v[140:141], v[82:83] neg_lo:[0,1] neg_hi:[0,1]
	v_pk_add_f32 v[244:245], v[142:143], v[80:81] neg_lo:[0,1] neg_hi:[0,1]
	v_pk_add_f32 v[246:247], v[142:143], v[82:83] neg_lo:[0,1] neg_hi:[0,1]
	v_pk_add_f32 v[104:105], v[140:141], v[72:73] neg_lo:[0,1] neg_hi:[0,1]
	v_pk_add_f32 v[106:107], v[140:141], v[74:75] neg_lo:[0,1] neg_hi:[0,1]
	v_pk_add_f32 v[248:249], v[142:143], v[72:73] neg_lo:[0,1] neg_hi:[0,1]
	v_pk_add_f32 v[250:251], v[142:143], v[74:75] neg_lo:[0,1] neg_hi:[0,1]
	v_mov_b32_e32 v202, s5
	v_sub_f32_e32 v202, s4, v202
	v_sub_f32_e32 v234, s4, v140
	v_sub_f32_e32 v235, s4, v142
	v_med3_f32 v234, v234, 0, v202
	v_med3_f32 v235, v235, 0, v202
	v_add_f32_e32 v231, v227, v234
	v_add_f32_e32 v230, v226, v235
	v_exp_f32_e64 v232, -v234
	v_exp_f32_e64 v233, -v235
	v_pk_add_f32 v[116:117], v[116:117], v[230:231] op_sel:[0,1] op_sel_hi:[1,1] neg_lo:[0,1] neg_hi:[0,1]
	v_pk_add_f32 v[118:119], v[118:119], v[230:231] op_sel:[0,1] op_sel_hi:[1,1] neg_lo:[0,1] neg_hi:[0,1]
	v_pk_add_f32 v[100:101], v[100:101], v[230:231] op_sel_hi:[1,0] neg_lo:[0,1] neg_hi:[0,1]
	v_pk_add_f32 v[102:103], v[102:103], v[230:231] op_sel_hi:[1,0] neg_lo:[0,1] neg_hi:[0,1]
	v_pk_add_f32 v[112:113], v[112:113], v[230:231] op_sel:[0,1] op_sel_hi:[1,1] neg_lo:[0,1] neg_hi:[0,1]
	v_pk_add_f32 v[114:115], v[114:115], v[230:231] op_sel:[0,1] op_sel_hi:[1,1] neg_lo:[0,1] neg_hi:[0,1]
	v_pk_add_f32 v[96:97], v[96:97], v[230:231] op_sel_hi:[1,0] neg_lo:[0,1] neg_hi:[0,1]
	v_pk_add_f32 v[98:99], v[98:99], v[230:231] op_sel_hi:[1,0] neg_lo:[0,1] neg_hi:[0,1]
	v_pk_add_f32 v[108:109], v[108:109], v[230:231] op_sel:[0,1] op_sel_hi:[1,1] neg_lo:[0,1] neg_hi:[0,1]
	v_pk_add_f32 v[110:111], v[110:111], v[230:231] op_sel:[0,1] op_sel_hi:[1,1] neg_lo:[0,1] neg_hi:[0,1]
	v_pk_add_f32 v[244:245], v[244:245], v[230:231] op_sel_hi:[1,0] neg_lo:[0,1] neg_hi:[0,1]
	v_pk_add_f32 v[246:247], v[246:247], v[230:231] op_sel_hi:[1,0] neg_lo:[0,1] neg_hi:[0,1]
	v_pk_add_f32 v[104:105], v[104:105], v[230:231] op_sel:[0,1] op_sel_hi:[1,1] neg_lo:[0,1] neg_hi:[0,1]
	v_pk_add_f32 v[106:107], v[106:107], v[230:231] op_sel:[0,1] op_sel_hi:[1,1] neg_lo:[0,1] neg_hi:[0,1]
	v_pk_add_f32 v[248:249], v[248:249], v[230:231] op_sel_hi:[1,0] neg_lo:[0,1] neg_hi:[0,1]
	v_pk_add_f32 v[250:251], v[250:251], v[230:231] op_sel_hi:[1,0] neg_lo:[0,1] neg_hi:[0,1]
	s_andn2_b64 vcc, exec, s[74:75]
	s_cbranch_vccnz .Lattn_nomask
	v_subrev_u32_e32 v234, s84, v136
	v_subrev_u32_e32 v235, s84, v138
	v_cmp_ge_i32_e64 s[4:5], v234, v122
	v_cmp_ge_i32_e64 s[72:73], v235, v122
	v_cmp_ge_i32_e64 s[74:75], v234, v204
	v_cndmask_b32_e64 v116, v201, v116, s[4:5]
	v_cmp_ge_i32_e64 s[4:5], v235, v204
	v_cndmask_b32_e64 v100, v201, v100, s[72:73]
	v_cmp_ge_i32_e64 s[72:73], v234, v205
	v_cndmask_b32_e64 v117, v201, v117, s[74:75]
	v_cmp_ge_i32_e64 s[74:75], v235, v205
	v_cndmask_b32_e64 v101, v201, v101, s[4:5]
	v_cmp_ge_i32_e64 s[4:5], v234, v206
	v_cndmask_b32_e64 v118, v201, v118, s[72:73]
	v_cmp_ge_i32_e64 s[72:73], v235, v206
	v_cndmask_b32_e64 v102, v201, v102, s[74:75]
	v_cmp_ge_i32_e64 s[74:75], v234, v207
	v_cndmask_b32_e64 v119, v201, v119, s[4:5]
	v_cmp_ge_i32_e64 s[4:5], v235, v207
	v_cndmask_b32_e64 v103, v201, v103, s[72:73]
	v_cmp_ge_i32_e64 s[72:73], v234, v208
	v_cndmask_b32_e64 v112, v201, v112, s[74:75]
	v_cmp_ge_i32_e64 s[74:75], v235, v208
	v_cndmask_b32_e64 v96, v201, v96, s[4:5]
	v_cmp_ge_i32_e64 s[4:5], v234, v209
	v_cndmask_b32_e64 v113, v201, v113, s[72:73]
	v_cmp_ge_i32_e64 s[72:73], v235, v209
	v_cndmask_b32_e64 v97, v201, v97, s[74:75]
	v_cmp_ge_i32_e64 s[74:75], v234, v210
	v_cndmask_b32_e64 v114, v201, v114, s[4:5]
	v_cmp_ge_i32_e64 s[4:5], v235, v210
	v_cndmask_b32_e64 v98, v201, v98, s[72:73]
	v_cmp_ge_i32_e64 s[72:73], v234, v123
	v_cndmask_b32_e64 v115, v201, v115, s[74:75]
	v_cmp_ge_i32_e64 s[74:75], v235, v123
	v_cndmask_b32_e64 v99, v201, v99, s[4:5]
	v_cmp_ge_i32_e64 s[4:5], v234, v211
	v_cndmask_b32_e64 v108, v201, v108, s[72:73]
	v_cmp_ge_i32_e64 s[72:73], v235, v211
	v_cndmask_b32_e64 v244, v201, v244, s[74:75]
	v_cmp_ge_i32_e64 s[74:75], v234, v212
	v_cndmask_b32_e64 v109, v201, v109, s[4:5]
	v_cmp_ge_i32_e64 s[4:5], v235, v212
	v_cndmask_b32_e64 v245, v201, v245, s[72:73]
	v_cmp_ge_i32_e64 s[72:73], v234, v213
	v_cndmask_b32_e64 v110, v201, v110, s[74:75]
	v_cmp_ge_i32_e64 s[74:75], v235, v213
	v_cndmask_b32_e64 v246, v201, v246, s[4:5]
	v_cmp_ge_i32_e64 s[4:5], v234, v214
	v_cndmask_b32_e64 v111, v201, v111, s[72:73]
	v_cmp_ge_i32_e64 s[72:73], v235, v214
	v_cndmask_b32_e64 v247, v201, v247, s[74:75]
	v_cmp_ge_i32_e64 s[74:75], v234, v215
	v_cndmask_b32_e64 v104, v201, v104, s[4:5]
	v_cmp_ge_i32_e64 s[4:5], v235, v215
	v_cndmask_b32_e64 v248, v201, v248, s[72:73]
	v_cmp_ge_i32_e64 s[72:73], v234, v216
	v_cndmask_b32_e64 v105, v201, v105, s[74:75]
	v_cmp_ge_i32_e64 s[74:75], v235, v216
	v_cndmask_b32_e64 v249, v201, v249, s[4:5]
	v_cmp_ge_i32_e64 s[4:5], v234, v217
	v_cndmask_b32_e64 v106, v201, v106, s[72:73]
	v_cmp_ge_i32_e64 s[72:73], v235, v217
	v_cndmask_b32_e64 v250, v201, v250, s[74:75]
	v_cndmask_b32_e64 v107, v201, v107, s[4:5]
	v_cndmask_b32_e64 v251, v201, v251, s[72:73]
.Lattn_nomask:
	s_waitcnt lgkmcnt(4)
	v_mfma_f32_16x16x32_bf16 v[116:119], v[88:91], v[0:3], v[116:119]
	v_mfma_f32_16x16x32_bf16 v[100:103], v[88:91], v[8:11], v[100:103]
	v_mfma_f32_16x16x32_bf16 v[112:115], v[164:167], v[0:3], v[112:115]
	v_mfma_f32_16x16x32_bf16 v[96:99], v[164:167], v[8:11], v[96:99]
	v_mfma_f32_16x16x32_bf16 v[116:119], v[92:95], v[4:7], v[116:119]
	v_mfma_f32_16x16x32_bf16 v[100:103], v[92:95], v[12:15], v[100:103]
	v_mfma_f32_16x16x32_bf16 v[112:115], v[168:171], v[4:7], v[112:115]
	v_mfma_f32_16x16x32_bf16 v[96:99], v[168:171], v[12:15], v[96:99]
	s_waitcnt lgkmcnt(0)
	v_mfma_f32_16x16x32_bf16 v[108:111], v[172:175], v[0:3], v[108:111]
	v_mfma_f32_16x16x32_bf16 v[244:247], v[172:175], v[8:11], v[244:247]
	v_mfma_f32_16x16x32_bf16 v[104:107], v[240:243], v[0:3], v[104:107]
	v_mfma_f32_16x16x32_bf16 v[248:251], v[240:243], v[8:11], v[248:251]
	v_mfma_f32_16x16x32_bf16 v[108:111], v[236:239], v[4:7], v[108:111]
	v_mfma_f32_16x16x32_bf16 v[244:247], v[236:239], v[12:15], v[244:247]
	v_mfma_f32_16x16x32_bf16 v[104:107], v[160:163], v[4:7], v[104:107]
	v_mfma_f32_16x16x32_bf16 v[248:251], v[160:163], v[12:15], v[248:251]
	ds_read_b128 v[88:91], v222 offset:9216
	ds_read_b128 v[92:95], v222 offset:9280
	ds_read_b128 v[164:167], v222 offset:11520
	ds_read_b128 v[168:171], v222 offset:11584
	ds_read_b128 v[172:175], v222 offset:13824
	ds_read_b128 v[236:239], v222 offset:13888
	ds_read_b128 v[240:243], v223 offset:9216
	ds_read_b128 v[160:163], v223 offset:9280
	v_max3_f32 v228, v116, v117, v118
	v_max3_f32 v229, v100, v101, v102
	v_max3_f32 v228, v228, v119, v112
	v_max3_f32 v229, v229, v103, v96
	v_max3_f32 v228, v228, v113, v114
	v_max3_f32 v229, v229, v97, v98
	v_max3_f32 v228, v228, v115, v108
	v_max3_f32 v229, v229, v99, v244
	v_max3_f32 v228, v228, v109, v110
	v_max3_f32 v229, v229, v245, v246
	v_max3_f32 v228, v228, v111, v104
	v_max3_f32 v229, v229, v247, v248
	v_max3_f32 v228, v228, v105, v106
	v_max3_f32 v229, v229, v249, v250
	v_max_f32_e32 v228, v228, v107
	v_max_f32_e32 v229, v229, v251
	v_max_f32_e32 v202, v228, v229
	v_cmp_lt_f32_e32 vcc, 0x42800000, v202
	s_cbranch_vccnz .Lattn_orig
	v_mov_b32_e32 v226, v230
	v_mov_b32_e32 v227, v231
	v_pk_mul_f32 v[52:53], v[52:53], v[232:233] op_sel_hi:[1,0]
	v_pk_mul_f32 v[54:55], v[54:55], v[232:233] op_sel_hi:[1,0]
	v_pk_mul_f32 v[44:45], v[44:45], v[232:233] op_sel_hi:[1,0]
	v_pk_mul_f32 v[46:47], v[46:47], v[232:233] op_sel_hi:[1,0]
	v_pk_mul_f32 v[40:41], v[40:41], v[232:233] op_sel_hi:[1,0]
	v_pk_mul_f32 v[42:43], v[42:43], v[232:233] op_sel_hi:[1,0]
	v_pk_mul_f32 v[48:49], v[48:49], v[232:233] op_sel_hi:[1,0]
	v_pk_mul_f32 v[50:51], v[50:51], v[232:233] op_sel_hi:[1,0]
	v_pk_mul_f32 v[36:37], v[36:37], v[232:233] op_sel:[0,1] op_sel_hi:[1,1]
	v_pk_mul_f32 v[38:39], v[38:39], v[232:233] op_sel:[0,1] op_sel_hi:[1,1]
	v_pk_mul_f32 v[28:29], v[28:29], v[232:233] op_sel:[0,1] op_sel_hi:[1,1]
	v_pk_mul_f32 v[30:31], v[30:31], v[232:233] op_sel:[0,1] op_sel_hi:[1,1]
	v_pk_mul_f32 v[16:17], v[16:17], v[232:233] op_sel:[0,1] op_sel_hi:[1,1]
	v_pk_mul_f32 v[18:19], v[18:19], v[232:233] op_sel:[0,1] op_sel_hi:[1,1]
	v_pk_mul_f32 v[32:33], v[32:33], v[232:233] op_sel:[0,1] op_sel_hi:[1,1]
	v_pk_mul_f32 v[34:35], v[34:35], v[232:233] op_sel:[0,1] op_sel_hi:[1,1]
	v_exp_f32_e32 v116, v116
	v_exp_f32_e32 v117, v117
	v_exp_f32_e32 v118, v118
	v_exp_f32_e32 v119, v119
	v_exp_f32_e32 v112, v112
	v_exp_f32_e32 v113, v113
	v_exp_f32_e32 v114, v114
	v_exp_f32_e32 v115, v115
	v_exp_f32_e32 v108, v108
	v_exp_f32_e32 v109, v109
	v_exp_f32_e32 v110, v110
	v_exp_f32_e32 v111, v111
	v_exp_f32_e32 v104, v104
	v_exp_f32_e32 v105, v105
	v_exp_f32_e32 v106, v106
	v_exp_f32_e32 v107, v107
	v_exp_f32_e32 v100, v100
	v_exp_f32_e32 v101, v101
	v_exp_f32_e32 v102, v102
	v_exp_f32_e32 v103, v103
	v_exp_f32_e32 v96, v96
	v_exp_f32_e32 v97, v97
	v_exp_f32_e32 v98, v98
	v_exp_f32_e32 v99, v99
	v_exp_f32_e32 v244, v244
	v_exp_f32_e32 v245, v245
	v_exp_f32_e32 v246, v246
	v_exp_f32_e32 v247, v247
	v_exp_f32_e32 v248, v248
	v_exp_f32_e32 v249, v249
	v_exp_f32_e32 v250, v250
	v_exp_f32_e32 v251, v251
	v_add_f32_e32 v228, 0, v116
	v_add_f32_e32 v229, 0, v100
	v_add_f32_e32 v228, v117, v228
	v_add_f32_e32 v229, v101, v229
	v_add_f32_e32 v228, v118, v228
	v_add_f32_e32 v229, v102, v229
	v_add_f32_e32 v228, v119, v228
	v_add_f32_e32 v229, v103, v229
	v_add_f32_e32 v228, v112, v228
	v_add_f32_e32 v229, v96, v229
	v_add_f32_e32 v228, v113, v228
	v_add_f32_e32 v229, v97, v229
	v_add_f32_e32 v228, v114, v228
	v_add_f32_e32 v229, v98, v229
	v_add_f32_e32 v228, v115, v228
	v_add_f32_e32 v229, v99, v229
	v_add_f32_e32 v228, v108, v228
	v_add_f32_e32 v229, v244, v229
	v_add_f32_e32 v228, v109, v228
	v_add_f32_e32 v229, v245, v229
	v_add_f32_e32 v228, v110, v228
	v_add_f32_e32 v229, v246, v229
	v_add_f32_e32 v228, v111, v228
	v_add_f32_e32 v229, v247, v229
	v_add_f32_e32 v228, v104, v228
	v_add_f32_e32 v229, v248, v229
	v_add_f32_e32 v228, v105, v228
	v_add_f32_e32 v229, v249, v229
	v_add_f32_e32 v228, v106, v228
	v_add_f32_e32 v229, v250, v229
	v_add_f32_e32 v228, v107, v228
	v_add_f32_e32 v229, v251, v229
	v_cvt_pk_bf16_f32 v76, v116, v117
	v_cvt_pk_bf16_f32 v77, v118, v119
	v_cvt_pk_bf16_f32 v78, v112, v113
	v_cvt_pk_bf16_f32 v79, v114, v115
	v_cvt_pk_bf16_f32 v84, v100, v101
	v_cvt_pk_bf16_f32 v85, v102, v103
	v_cvt_pk_bf16_f32 v86, v96, v97
	v_cvt_pk_bf16_f32 v87, v98, v99
	v_cvt_pk_bf16_f32 v72, v108, v109
	v_cvt_pk_bf16_f32 v73, v110, v111
	v_cvt_pk_bf16_f32 v74, v104, v105
	v_cvt_pk_bf16_f32 v75, v106, v107
	v_cvt_pk_bf16_f32 v80, v244, v245
	v_cvt_pk_bf16_f32 v81, v246, v247
	v_cvt_pk_bf16_f32 v82, v248, v249
	v_cvt_pk_bf16_f32 v83, v250, v251
	v_fma_f32 v225, v225, v232, v228
	v_fma_f32 v224, v224, v233, v229
	s_nop 1
	s_waitcnt lgkmcnt(7)
	v_mfma_f32_16x16x32_bf16 v[52:55], v[88:91], v[76:79], v[52:55]
	v_mfma_f32_16x16x32_bf16 v[36:39], v[88:91], v[84:87], v[36:39]
	s_waitcnt lgkmcnt(6)
	v_mfma_f32_16x16x32_bf16 v[52:55], v[92:95], v[72:75], v[52:55]
	v_mfma_f32_16x16x32_bf16 v[36:39], v[92:95], v[80:83], v[36:39]
	s_waitcnt lgkmcnt(5)
	v_mfma_f32_16x16x32_bf16 v[44:47], v[164:167], v[76:79], v[44:47]
	v_mfma_f32_16x16x32_bf16 v[28:31], v[164:167], v[84:87], v[28:31]
	s_waitcnt lgkmcnt(4)
	v_mfma_f32_16x16x32_bf16 v[44:47], v[168:171], v[72:75], v[44:47]
	v_mfma_f32_16x16x32_bf16 v[28:31], v[168:171], v[80:83], v[28:31]
	s_waitcnt lgkmcnt(3)
	v_mfma_f32_16x16x32_bf16 v[40:43], v[172:175], v[76:79], v[40:43]
	v_mfma_f32_16x16x32_bf16 v[16:19], v[172:175], v[84:87], v[16:19]
	s_waitcnt lgkmcnt(2)
	v_mfma_f32_16x16x32_bf16 v[40:43], v[236:239], v[72:75], v[40:43]
	v_mfma_f32_16x16x32_bf16 v[16:19], v[236:239], v[80:83], v[16:19]
	s_waitcnt lgkmcnt(1)
	v_mfma_f32_16x16x32_bf16 v[48:51], v[240:243], v[76:79], v[48:51]
	v_mfma_f32_16x16x32_bf16 v[32:35], v[240:243], v[84:87], v[32:35]
	s_waitcnt lgkmcnt(0)
	v_mfma_f32_16x16x32_bf16 v[48:51], v[160:163], v[72:75], v[48:51]
	v_mfma_f32_16x16x32_bf16 v[32:35], v[160:163], v[80:83], v[32:35]
	s_branch .LBB0_883
